# v86 + RG-LRU pass-2 gate evaluations of token tiles 0-2 list-scheduled with temporaries renamed into registers that are dead at that point (same instructions)
# baseline (speedup 1.0000x reference)
; #define LAS __attribute__((address_space(3)))
; __device__ __forceinline__ float bf2f(unsigned short v) { return __uint_as_float(((unsigned)v) << 16); }
; template <int PASS>
; __device__ __forceinline__ void rglru_phase(const Ctx& F, int l, const bf16_t* XRb, bf16_t* GRb, bool latent_only = false) {
;     ...
;             if (PASS == 2) { const bf16_t* gp = GRb + (size_t)(seg_row0 + tl0 + lane) * 1024 + blk * 128 + cw; g0 = *(const u32x4*)gp; g1 = *(const u32x4*)(gp + 8); }
;             float aggA[2] = {1.f, 1.f}, aggB[2] = {0.f, 0.f};
;             float hF = PASS == 2 ? CAR[(0 * 9 + (c - c0)) * 16 + l15] : 0.f;
;             float hfv[4][4], ba_[4][4], bb_[4][4], bAe[4], bBe[4], bAt[4], bBt[4];
; #pragma unroll
;             for (int mt = 0; mt < 4; ++mt) {
;                 f32x4 ag[4];
; #pragma unroll
;                 for (int gt = 0; gt < 4; ++gt) { const float nb = (gt & 1) ? nbx[gt >> 1] : nba[gt >> 1]; ag[gt] = (f32x4){nb, nb, nb, nb}; }
; #pragma unroll
;                 for (int ks = 0; ks < 4; ++ks) { const bf16x8 af = *(const LAS bf16x8*)(XT + (mt * 16 + l15) * XT_LD + ks * 32 + 8 * l4);
; #pragma unroll
;                     for (int gt = 0; gt < 4; ++gt) ag[gt] = __builtin_amdgcn_mfma_f32_16x16x32_bf16(af, Bf[gt][ks], ag[gt], 0, 0, 0); }
;                 float ea[2][4], eb[2][4];
; #pragma unroll
;                 for (int r = 0; r < 4; ++r) { const int tok = mt * 16 + 4 * l4 + r;
;                     const float xv = bf2f(XT[tok * XT_LD + cw + l15]);
; #pragma unroll
;                     for (int d = 0; d < 2; ++d) {
;                         const float e1 = 1.0f + __builtin_amdgcn_exp2f(ag[2 * d][r]), e2 = 1.0f + __builtin_amdgcn_exp2f(ag[2 * d + 1][r]);
;                         const float inv = __builtin_amdgcn_rcpf(e1 * e2); const float rgate = e2 * inv, igate = e1 * inv;
;                         const float a = __builtin_amdgcn_exp2f(rgate * cl2[d]);
;                         const float om = fmaf(-a, a, 1.0f);
;                         const float bv = __builtin_amdgcn_sqrtf(om) * (igate * xv);
;                         ea[d][r] = a; eb[d][r] = bv; } }
.LBB0_509:
	s_add_i32 s18, s39, 0xffffff00
	s_cmp_lt_u32 s38, 4
	s_cselect_b32 s19, s22, s23
	s_cselect_b32 s18, s39, s18
	s_add_i32 s18, s18, s19
	v_add_u32_e32 v34, s18, v166
	v_ashrrev_i32_e32 v35, 31, v34
	v_lshlrev_b64 v[34:35], 11, v[34:35]
	v_lshl_add_u64 v[34:35], s[20:21], 0, v[34:35]
	global_load_dwordx4 v[116:119], v[34:35], off offset:16
	global_load_dwordx4 v[120:123], v[34:35], off
	ds_read_b32 v201, v187
	ds_read_b128 v[124:127], v180
	ds_read_b128 v[160:163], v180 offset:64
	ds_read_u16 v32, v181
	s_waitcnt lgkmcnt(2)
	v_mfma_f32_16x16x32_bf16 v[128:131], v[124:127], v[0:3], v[100:103]
	s_and_b64 vcc, exec, s[62:63]
	s_mov_b32 s39, s33
	s_mov_b32 s38, s8
	v_mfma_f32_16x16x32_bf16 v[132:135], v[124:127], v[16:19], v[104:107]
	v_mfma_f32_16x16x32_bf16 v[136:139], v[124:127], v[36:39], v[108:111]
	v_mfma_f32_16x16x32_bf16 v[124:127], v[124:127], v[52:55], v[112:115]
	s_waitcnt lgkmcnt(1)
	v_mfma_f32_16x16x32_bf16 v[128:131], v[160:163], v[4:7], v[128:131]
	v_mfma_f32_16x16x32_bf16 v[132:135], v[160:163], v[20:23], v[132:135]
	v_mfma_f32_16x16x32_bf16 v[136:139], v[160:163], v[40:43], v[136:139]
	v_mfma_f32_16x16x32_bf16 v[124:127], v[160:163], v[56:59], v[124:127]
	ds_read_b128 v[160:163], v180 offset:128
	s_waitcnt lgkmcnt(0)
	v_mfma_f32_16x16x32_bf16 v[128:131], v[160:163], v[8:11], v[128:131]
	v_mfma_f32_16x16x32_bf16 v[132:135], v[160:163], v[24:27], v[132:135]
	v_mfma_f32_16x16x32_bf16 v[188:191], v[160:163], v[44:47], v[136:139]
	v_mfma_f32_16x16x32_bf16 v[124:127], v[160:163], v[60:63], v[124:127]
	ds_read_b128 v[160:163], v180 offset:192
	s_waitcnt lgkmcnt(0)
	v_mfma_f32_16x16x32_bf16 v[136:139], v[160:163], v[12:15], v[128:131]
	v_mfma_f32_16x16x32_bf16 v[132:135], v[160:163], v[28:31], v[132:135]
	v_mfma_f32_16x16x32_bf16 v[128:131], v[160:163], v[48:51], v[188:191]
	v_mfma_f32_16x16x32_bf16 v[124:127], v[160:163], v[64:67], v[124:127]
	s_nop 7
	ds_read_b128 v[160:163], v180 offset:4416
	v_exp_f32_e32 v128, v128
	v_exp_f32_e32 v124, v124
	v_exp_f32_e32 v126, v126
	v_add_f32_e32 v128, 1.0, v128
	v_exp_f32_e32 v222, v130
	v_add_f32_e32 v124, 1.0, v124
	v_exp_f32_e32 v200, v136
	ds_read_u16 v207, v181 offset:272
	v_mul_f32_e32 v204, v128, v124
	v_exp_f32_e32 v132, v132
	v_rcp_f32_e32 v204, v204
	v_exp_f32_e32 v133, v133
	v_exp_f32_e32 v206, v137
	v_mul_f32_e32 v124, v124, v204
	v_exp_f32_e32 v212, v134
	ds_read_u16 v215, v181 offset:544
	v_exp_f32_e32 v214, v138
	v_add_f32_e32 v126, 1.0, v126
	v_mul_f32_e32 v124, v186, v124
	v_add_f32_e32 v222, 1.0, v222
	v_exp_f32_e32 v224, v139
	v_exp_f32_e32 v226, v135
	v_add_f32_e32 v200, 1.0, v200
	v_add_f32_e32 v132, 1.0, v132
	ds_read_u16 v227, v181 offset:816
	v_add_f32_e32 v133, 1.0, v133
	v_exp_f32_e32 v125, v125
	v_exp_f32_e32 v127, v127
	v_exp_f32_e32 v188, v124
	v_add_f32_e32 v206, 1.0, v206
	v_exp_f32_e32 v210, v129
	v_mul_f32_e32 v223, v222, v126
	v_exp_f32_e32 v230, v131
	v_mul_f32_e32 v202, v200, v132
	v_mul_f32_e32 v208, v206, v133
	v_add_f32_e32 v212, 1.0, v212
	v_add_f32_e32 v214, 1.0, v214
	v_rcp_f32_e32 v223, v223
	v_rcp_f32_e32 v202, v202
	v_rcp_f32_e32 v208, v208
	v_mul_f32_e32 v220, v214, v212
	v_add_f32_e32 v224, 1.0, v224
	v_add_f32_e32 v226, 1.0, v226
	v_add_f32_e32 v125, 1.0, v125
	v_add_f32_e32 v127, 1.0, v127
	v_fma_f32 v205, -v188, v188, 1.0
	v_add_f32_e32 v210, 1.0, v210
	v_rcp_f32_e32 v220, v220
	v_mul_f32_e32 v228, v224, v226
	v_add_f32_e32 v230, 1.0, v230
	v_sqrt_f32_e32 v205, v205
	v_mul_f32_e32 v211, v210, v125
	v_mul_f32_e32 v126, v126, v223
	v_rcp_f32_e32 v228, v228
	v_mul_f32_e32 v231, v230, v127
	v_lshlrev_b32_e32 v199, 16, v32
	v_mul_f32_e32 v132, v132, v202
	v_mul_f32_e32 v128, v128, v204
	v_mul_f32_e32 v133, v133, v208
	v_rcp_f32_e32 v211, v211
	v_mul_f32_e32 v126, v186, v126
	v_rcp_f32_e32 v231, v231
	v_mul_f32_e32 v132, v185, v132
	v_mul_f32_e32 v128, v128, v199
	v_mul_f32_e32 v133, v185, v133
	v_mul_f32_e32 v212, v212, v220
	v_exp_f32_e32 v194, v126
	v_exp_f32_e32 v132, v132
	v_mul_f32_e32 v189, v128, v205
	v_exp_f32_e32 v133, v133
	v_mul_f32_e32 v212, v185, v212
	v_mul_f32_e32 v226, v226, v228
	v_mul_f32_e32 v125, v125, v211
	v_exp_f32_e32 v128, v212
	v_mul_f32_e32 v226, v185, v226
	v_mul_f32_e32 v127, v127, v231
	v_mul_f32_e32 v125, v186, v125
	v_exp_f32_e32 v126, v226
	v_mul_f32_e32 v127, v186, v127
	v_fma_f32 v203, -v132, v132, 1.0
	v_fma_f32 v209, -v133, v133, 1.0
	v_exp_f32_e32 v191, v125
	v_exp_f32_e32 v197, v127
	v_sqrt_f32_e32 v203, v203
	v_sqrt_f32_e32 v209, v209
	v_fma_f32 v221, -v128, v128, 1.0
	v_mul_f32_e32 v200, v200, v202
	s_waitcnt lgkmcnt(2)
	v_lshlrev_b32_e32 v207, 16, v207
	v_mul_f32_e32 v206, v206, v208
	v_sqrt_f32_e32 v221, v221
	v_fma_f32 v229, -v126, v126, 1.0
	v_mul_f32_e32 v200, v200, v199
	v_mul_f32_e32 v206, v206, v207
	v_fma_f32 v213, -v191, v191, 1.0
	s_waitcnt lgkmcnt(1)
	v_lshlrev_b32_e32 v215, 16, v215
	v_mul_f32_e32 v214, v214, v220
	v_fma_f32 v225, -v194, v194, 1.0
	v_sqrt_f32_e32 v229, v229
	v_fma_f32 v233, -v197, v197, 1.0
	v_mul_f32_e32 v32, v200, v203
	v_mul_f32_e32 v190, v206, v209
	v_sqrt_f32_e32 v213, v213
	v_mul_f32_e32 v214, v214, v215
	v_sqrt_f32_e32 v225, v225
	s_waitcnt lgkmcnt(0)
	v_lshlrev_b32_e32 v227, 16, v227
	v_mul_f32_e32 v224, v224, v228
	v_sqrt_f32_e32 v233, v233
	v_mul_f32_e32 v210, v210, v211
	v_mul_f32_e32 v193, v214, v221
	v_mul_f32_e32 v222, v222, v223
	v_mul_f32_e32 v224, v224, v227
	v_mul_f32_e32 v230, v230, v231
	v_mul_f32_e32 v232, v132, v133
	v_fma_f32 v234, v133, v32, v190
	v_mul_f32_e32 v207, v210, v207
	v_mul_f32_e32 v215, v222, v215
	v_mul_f32_e32 v196, v224, v229
	v_mul_f32_e32 v227, v230, v227
	v_mul_f32_e32 v232, v128, v232
	v_fma_f32 v234, v128, v234, v193
	v_mul_f32_e32 v192, v207, v213
	v_mul_f32_e32 v195, v215, v225
	v_mul_f32_e32 v125, v126, v232
	v_mul_f32_e32 v198, v227, v233
	v_fma_f32 v124, v126, v234, v196
	ds_bpermute_b32 v127, v155, v125
	ds_bpermute_b32 v129, v155, v124
	s_waitcnt lgkmcnt(1)
; template <int PASS>
; __device__ __forceinline__ void rglru_phase(const Ctx& F, int l, const bf16_t* XRb, bf16_t* GRb, bool latent_only = false) {
;     ...
;             for (int mt = 0; mt < 4; ++mt) {
;                 f32x4 ag[4];
; #pragma unroll
;                 for (int gt = 0; gt < 4; ++gt) { const float nb = (gt & 1) ? nbx[gt >> 1] : nba[gt >> 1]; ag[gt] = (f32x4){nb, nb, nb, nb}; }
; #pragma unroll
;                 for (int ks = 0; ks < 4; ++ks) { const bf16x8 af = *(const LAS bf16x8*)(XT + (mt * 16 + l15) * XT_LD + ks * 32 + 8 * l4);
; #pragma unroll
;                     for (int gt = 0; gt < 4; ++gt) ag[gt] = __builtin_amdgcn_mfma_f32_16x16x32_bf16(af, Bf[gt][ks], ag[gt], 0, 0, 0); }
;                 float ea[2][4], eb[2][4];
; #pragma unroll
;                 for (int r = 0; r < 4; ++r) { const int tok = mt * 16 + 4 * l4 + r;
;                     const float xv = bf2f(XT[tok * XT_LD + cw + l15]);
; #pragma unroll
;                     for (int d = 0; d < 2; ++d) {
;                         const float e1 = 1.0f + __builtin_amdgcn_exp2f(ag[2 * d][r]), e2 = 1.0f + __builtin_amdgcn_exp2f(ag[2 * d + 1][r]);
;                         const float inv = __builtin_amdgcn_rcpf(e1 * e2); const float rgate = e2 * inv, igate = e1 * inv;
;                         const float a = __builtin_amdgcn_exp2f(rgate * cl2[d]);
;                         const float om = fmaf(-a, a, 1.0f);
;                         const float bv = __builtin_amdgcn_sqrtf(om) * (igate * xv);
;                         ea[d][r] = a; eb[d][r] = bv; } }
;     ...
;                         { const float Ap = BPF(lane - 16, A), Bp = BPF(lane - 16, B); if (l4 >= 1) { B = A * Bp + B; A = A * Ap; } }
;                         { const float Ap = BPF(lane - 32, A), Bp = BPF(lane - 32, B); if (l4 >= 2) { B = A * Bp + B; A = A * Ap; } }
;                         const float At = BPF(48 + l15, A), Bt = BPF(48 + l15, B);
;                         float Ae = BPF(lane - 16, A), Be = BPF(lane - 16, B); if (l4 == 0) { Ae = 1.f; Be = 0.f; }
;                         float h = Ae * hF + Be;
; #pragma unroll
;                         for (int r = 0; r < 4; ++r) { h = ea[0][r] * h + eb[0][r]; hfv[mt][r] = h; }
;                         hF = At * hF + Bt;
;                     }
;                     {
;                         float A = ea[1][3], B = eb[1][3];
; #pragma unroll
	v_mul_f32_e32 v127, v125, v127
	s_waitcnt lgkmcnt(0)
	v_fma_f32 v129, v125, v129, v124
	v_cndmask_b32_e64 v125, v125, v127, s[48:49]
	v_cndmask_b32_e64 v124, v124, v129, s[48:49]
	ds_bpermute_b32 v127, v156, v125
	ds_bpermute_b32 v129, v156, v124
	s_waitcnt lgkmcnt(1)
	v_mul_f32_e32 v127, v125, v127
	s_waitcnt lgkmcnt(0)
	v_fma_f32 v129, v125, v129, v124
	v_cndmask_b32_e64 v125, v125, v127, s[50:51]
	v_cndmask_b32_e64 v124, v124, v129, s[50:51]
	ds_bpermute_b32 v127, v158, v125
	ds_bpermute_b32 v225, v158, v124
	ds_bpermute_b32 v125, v155, v125
	ds_bpermute_b32 v124, v155, v124
	s_waitcnt lgkmcnt(2)
	v_fmac_f32_e32 v225, v201, v127
	s_waitcnt lgkmcnt(1)
	v_cndmask_b32_e64 v125, v125, 1.0, s[52:53]
	s_waitcnt lgkmcnt(0)
	v_cndmask_b32_e64 v124, v124, 0, s[52:53]
	v_fmac_f32_e32 v124, v201, v125
	v_fmac_f32_e32 v32, v132, v124
	v_fma_f32 v124, v194, v198, v195
	v_mul_f32_e32 v125, v197, v194
	v_fmac_f32_e32 v190, v133, v32
	v_fma_f32 v124, v191, v124, v192
	v_mul_f32_e32 v125, v191, v125
	v_fmac_f32_e32 v193, v128, v190
	v_fma_f32 v124, v188, v124, v189
	v_mul_f32_e32 v125, v188, v125
	v_fmac_f32_e32 v196, v126, v193
	ds_bpermute_b32 v126, v159, v125
	ds_bpermute_b32 v128, v159, v124
	s_waitcnt lgkmcnt(1)
	v_mul_f32_e32 v126, v125, v126
	s_waitcnt lgkmcnt(0)
	v_fma_f32 v128, v125, v128, v124
	v_cndmask_b32_e64 v125, v125, v126, s[54:55]
	v_cndmask_b32_e64 v124, v124, v128, s[54:55]
	ds_bpermute_b32 v126, v156, v125
	ds_bpermute_b32 v128, v156, v124
	s_waitcnt lgkmcnt(1)
	v_mul_f32_e32 v126, v125, v126
	s_waitcnt lgkmcnt(0)
	v_fma_f32 v128, v125, v128, v124
	v_cndmask_b32_e64 v125, v125, v126, s[56:57]
	v_cndmask_b32_e64 v124, v124, v128, s[56:57]
	ds_bpermute_b32 v125, v159, v125
	ds_bpermute_b32 v124, v159, v124
	s_waitcnt lgkmcnt(1)
	v_cndmask_b32_e64 v200, v125, 1.0, s[58:59]
	s_waitcnt lgkmcnt(0)
	v_cndmask_b32_e64 v199, v124, 0, s[58:59]
	ds_read_b128 v[124:127], v180 offset:4352
	s_waitcnt lgkmcnt(0)
	v_mfma_f32_16x16x32_bf16 v[128:131], v[124:127], v[0:3], v[100:103]
	v_mfma_f32_16x16x32_bf16 v[132:135], v[124:127], v[16:19], v[104:107]
	v_mfma_f32_16x16x32_bf16 v[136:139], v[124:127], v[36:39], v[108:111]
	v_mfma_f32_16x16x32_bf16 v[124:127], v[124:127], v[52:55], v[112:115]
	v_mfma_f32_16x16x32_bf16 v[128:131], v[160:163], v[4:7], v[128:131]
	v_mfma_f32_16x16x32_bf16 v[132:135], v[160:163], v[20:23], v[132:135]
	v_mfma_f32_16x16x32_bf16 v[136:139], v[160:163], v[40:43], v[136:139]
	v_mfma_f32_16x16x32_bf16 v[124:127], v[160:163], v[56:59], v[124:127]
	ds_read_b128 v[160:163], v180 offset:4480
	s_waitcnt lgkmcnt(0)
	v_mfma_f32_16x16x32_bf16 v[128:131], v[160:163], v[8:11], v[128:131]
	v_mfma_f32_16x16x32_bf16 v[132:135], v[160:163], v[24:27], v[132:135]
	v_mfma_f32_16x16x32_bf16 v[202:205], v[160:163], v[44:47], v[136:139]
	v_mfma_f32_16x16x32_bf16 v[124:127], v[160:163], v[60:63], v[124:127]
	ds_read_b128 v[160:163], v180 offset:4544
	s_waitcnt lgkmcnt(0)
	v_mfma_f32_16x16x32_bf16 v[136:139], v[160:163], v[12:15], v[128:131]
	s_nop 7
	v_exp_f32_e32 v136, v136
	v_mfma_f32_16x16x32_bf16 v[132:135], v[160:163], v[28:31], v[132:135]
	v_add_f32_e32 v136, 1.0, v136
	v_mfma_f32_16x16x32_bf16 v[128:131], v[160:163], v[48:51], v[202:205]
	v_mfma_f32_16x16x32_bf16 v[124:127], v[160:163], v[64:67], v[124:127]
	s_nop 7
	ds_read_u16 v213, v181 offset:4352
	v_exp_f32_e32 v132, v132
	v_exp_f32_e32 v128, v128
	v_exp_f32_e32 v124, v124
	v_add_f32_e32 v132, 1.0, v132
	v_exp_f32_e32 v129, v129
	v_mul_f32_e32 v214, v136, v132
	v_add_f32_e32 v128, 1.0, v128
	ds_read_b128 v[160:163], v180 offset:8768
	v_add_f32_e32 v124, 1.0, v124
	v_rcp_f32_e32 v214, v214
	v_mul_f32_e32 v220, v128, v124
	v_exp_f32_e32 v125, v125
	v_rcp_f32_e32 v220, v220
	v_mul_f32_e32 v132, v132, v214
	v_exp_f32_e32 v133, v133
	ds_read_u16 v222, v181 offset:4624
	v_mul_f32_e32 v132, v185, v132
	v_mul_f32_e32 v124, v124, v220
	v_exp_f32_e32 v132, v132
	v_mul_f32_e32 v124, v186, v124
	v_exp_f32_e32 v224, v137
	v_exp_f32_e32 v202, v124
	s_waitcnt lgkmcnt(2)
	v_lshlrev_b32_e32 v213, 16, v213
	v_mul_f32_e32 v136, v136, v214
	ds_read_u16 v232, v181 offset:4896
	v_fma_f32 v215, -v132, v132, 1.0
	v_add_f32_e32 v129, 1.0, v129
	v_add_f32_e32 v125, 1.0, v125
	v_mul_f32_e32 v128, v128, v220
	v_exp_f32_e32 v230, v134
	v_exp_f32_e32 v234, v138
	v_mul_f32_e32 v136, v136, v213
	v_sqrt_f32_e32 v215, v215
	ds_read_u16 v214, v181 offset:5168
	v_mul_f32_e32 v128, v128, v213
	v_fma_f32 v221, -v202, v202, 1.0
	v_mul_f32_e32 v229, v129, v125
	v_exp_f32_e32 v240, v135
	v_exp_f32_e32 v242, v139
	v_add_f32_e32 v133, 1.0, v133
	v_exp_f32_e32 v126, v126
	v_sqrt_f32_e32 v221, v221
	v_exp_f32_e32 v127, v127
	v_add_f32_e32 v224, 1.0, v224
	v_rcp_f32_e32 v229, v229
	v_exp_f32_e32 v238, v130
	v_exp_f32_e32 v213, v131
	v_mul_f32_e32 v226, v224, v133
	v_add_f32_e32 v230, 1.0, v230
	v_add_f32_e32 v234, 1.0, v234
	v_mul_f32_e32 v201, v136, v215
	v_rcp_f32_e32 v226, v226
	v_mul_f32_e32 v235, v234, v230
	v_add_f32_e32 v240, 1.0, v240
	v_add_f32_e32 v242, 1.0, v242
	v_add_f32_e32 v126, 1.0, v126
	v_mul_f32_e32 v203, v128, v221
	v_add_f32_e32 v127, 1.0, v127
	v_mul_f32_e32 v125, v125, v229
	v_rcp_f32_e32 v235, v235
	v_add_f32_e32 v238, 1.0, v238
	v_mul_f32_e32 v215, v242, v240
	v_add_f32_e32 v213, 1.0, v213
	v_mul_f32_e32 v125, v186, v125
	v_mul_f32_e32 v239, v238, v126
	v_rcp_f32_e32 v215, v215
	v_mul_f32_e32 v221, v213, v127
	v_mul_f32_e32 v133, v133, v226
	v_exp_f32_e32 v205, v125
	v_rcp_f32_e32 v239, v239
	v_rcp_f32_e32 v221, v221
	s_waitcnt lgkmcnt(2)
; template <int PASS>
; __device__ __forceinline__ void rglru_phase(const Ctx& F, int l, const bf16_t* XRb, bf16_t* GRb, bool latent_only = false) {
;     ...
;             for (int mt = 0; mt < 4; ++mt) {
;                 f32x4 ag[4];
; #pragma unroll
;                 for (int gt = 0; gt < 4; ++gt) { const float nb = (gt & 1) ? nbx[gt >> 1] : nba[gt >> 1]; ag[gt] = (f32x4){nb, nb, nb, nb}; }
; #pragma unroll
;                 for (int ks = 0; ks < 4; ++ks) { const bf16x8 af = *(const LAS bf16x8*)(XT + (mt * 16 + l15) * XT_LD + ks * 32 + 8 * l4);
; #pragma unroll
;                     for (int gt = 0; gt < 4; ++gt) ag[gt] = __builtin_amdgcn_mfma_f32_16x16x32_bf16(af, Bf[gt][ks], ag[gt], 0, 0, 0); }
;                 float ea[2][4], eb[2][4];
; #pragma unroll
;                 for (int r = 0; r < 4; ++r) { const int tok = mt * 16 + 4 * l4 + r;
;                     const float xv = bf2f(XT[tok * XT_LD + cw + l15]);
; #pragma unroll
;                     for (int d = 0; d < 2; ++d) {
;                         const float e1 = 1.0f + __builtin_amdgcn_exp2f(ag[2 * d][r]), e2 = 1.0f + __builtin_amdgcn_exp2f(ag[2 * d + 1][r]);
;                         const float inv = __builtin_amdgcn_rcpf(e1 * e2); const float rgate = e2 * inv, igate = e1 * inv;
;                         const float a = __builtin_amdgcn_exp2f(rgate * cl2[d]);
;                         const float om = fmaf(-a, a, 1.0f);
;                         const float bv = __builtin_amdgcn_sqrtf(om) * (igate * xv);
;                         ea[d][r] = a; eb[d][r] = bv; } }
;     ...
;                         { const float Ap = BPF(lane - 16, A), Bp = BPF(lane - 16, B); if (l4 >= 1) { B = A * Bp + B; A = A * Ap; } }
;                         { const float Ap = BPF(lane - 32, A), Bp = BPF(lane - 32, B); if (l4 >= 2) { B = A * Bp + B; A = A * Ap; } }
;                         const float At = BPF(48 + l15, A), Bt = BPF(48 + l15, B);
;                         float Ae = BPF(lane - 16, A), Be = BPF(lane - 16, B); if (l4 == 0) { Ae = 1.f; Be = 0.f; }
;                         float h = Ae * hF + Be;
; #pragma unroll
;                         for (int r = 0; r < 4; ++r) { h = ea[0][r] * h + eb[0][r]; hfv[mt][r] = h; }
;                         hF = At * hF + Bt;
;                     }
;                     {
;                         float A = ea[1][3], B = eb[1][3];
; #pragma unroll
	v_lshlrev_b32_e32 v223, 16, v222
	v_mul_f32_e32 v226, v224, v226
	v_mul_f32_e32 v227, v185, v133
	v_mul_f32_e32 v230, v230, v235
	v_exp_f32_e32 v124, v227
	v_mul_f32_e32 v226, v226, v223
	v_mul_f32_e32 v129, v129, v229
	v_mul_f32_e32 v236, v185, v230
	v_mul_f32_e32 v240, v240, v215
	v_mul_f32_e32 v223, v129, v223
	v_exp_f32_e32 v125, v236
	v_mul_f32_e32 v126, v126, v239
	v_mul_f32_e32 v240, v185, v240
	v_mul_f32_e32 v127, v127, v221
	v_mul_f32_e32 v126, v186, v126
	v_exp_f32_e32 v129, v240
	v_mul_f32_e32 v127, v186, v127
	v_fma_f32 v228, -v124, v124, 1.0
	v_exp_f32_e32 v208, v126
	v_exp_f32_e32 v211, v127
	v_sqrt_f32_e32 v228, v228
	v_fma_f32 v237, -v125, v125, 1.0
	v_fma_f32 v220, -v129, v129, 1.0
	v_sqrt_f32_e32 v237, v237
	v_fma_f32 v231, -v205, v205, 1.0
	s_waitcnt lgkmcnt(1)
	v_lshlrev_b32_e32 v233, 16, v232
	v_mul_f32_e32 v235, v234, v235
	v_fma_f32 v241, -v208, v208, 1.0
	v_sqrt_f32_e32 v220, v220
	v_fma_f32 v222, -v211, v211, 1.0
	v_mul_f32_e32 v204, v226, v228
	v_sqrt_f32_e32 v231, v231
	v_mul_f32_e32 v235, v235, v233
	v_sqrt_f32_e32 v241, v241
	s_waitcnt lgkmcnt(0)
	v_lshlrev_b32_e32 v214, 16, v214
	v_mul_f32_e32 v242, v242, v215
	v_sqrt_f32_e32 v222, v222
	v_mul_f32_e32 v207, v235, v237
	v_mul_f32_e32 v238, v238, v239
	v_mul_f32_e32 v242, v242, v214
	v_mul_f32_e32 v213, v213, v221
	v_fma_f32 v224, v124, v201, v204
	v_mul_f32_e32 v227, v132, v124
	v_mul_f32_e32 v233, v238, v233
	v_mul_f32_e32 v210, v242, v220
	v_mul_f32_e32 v214, v213, v214
	v_fma_f32 v224, v125, v224, v207
	v_mul_f32_e32 v227, v125, v227
	v_mul_f32_e32 v206, v223, v231
	v_mul_f32_e32 v209, v233, v241
	v_mul_f32_e32 v212, v214, v222
	v_fma_f32 v126, v129, v224, v210
	v_mul_f32_e32 v127, v129, v227
	ds_bpermute_b32 v128, v155, v127
	ds_bpermute_b32 v130, v155, v126
	s_waitcnt lgkmcnt(1)
	v_mul_f32_e32 v128, v127, v128
	s_waitcnt lgkmcnt(0)
	v_fma_f32 v130, v127, v130, v126
	v_cndmask_b32_e64 v127, v127, v128, s[48:49]
	v_cndmask_b32_e64 v126, v126, v130, s[48:49]
	ds_bpermute_b32 v128, v156, v127
	ds_bpermute_b32 v130, v156, v126
	s_waitcnt lgkmcnt(1)
	v_mul_f32_e32 v128, v127, v128
	s_waitcnt lgkmcnt(0)
	v_fma_f32 v130, v127, v130, v126
	v_cndmask_b32_e64 v127, v127, v128, s[50:51]
	v_cndmask_b32_e64 v126, v126, v130, s[50:51]
	ds_bpermute_b32 v128, v158, v127
	ds_bpermute_b32 v242, v158, v126
	ds_bpermute_b32 v127, v155, v127
	ds_bpermute_b32 v126, v155, v126
	s_waitcnt lgkmcnt(2)
	v_fmac_f32_e32 v242, v225, v128
	s_waitcnt lgkmcnt(1)
	v_cndmask_b32_e64 v127, v127, 1.0, s[52:53]
	s_waitcnt lgkmcnt(0)
	v_cndmask_b32_e64 v126, v126, 0, s[52:53]
	v_fmac_f32_e32 v126, v225, v127
	v_fmac_f32_e32 v201, v132, v126
	v_fmac_f32_e32 v204, v124, v201
	v_fmac_f32_e32 v207, v125, v204
	v_fma_f32 v124, v208, v212, v209
	v_mul_f32_e32 v125, v211, v208
	v_fma_f32 v124, v205, v124, v206
	v_mul_f32_e32 v125, v205, v125
	v_fma_f32 v124, v202, v124, v203
	v_mul_f32_e32 v125, v202, v125
	ds_bpermute_b32 v126, v159, v125
	ds_bpermute_b32 v127, v159, v124
	v_fmac_f32_e32 v210, v129, v207
	s_waitcnt lgkmcnt(1)
	v_mul_f32_e32 v126, v125, v126
	s_waitcnt lgkmcnt(0)
	v_fma_f32 v127, v125, v127, v124
	v_cndmask_b32_e64 v125, v125, v126, s[54:55]
	v_cndmask_b32_e64 v124, v124, v127, s[54:55]
	ds_bpermute_b32 v126, v156, v125
	ds_bpermute_b32 v127, v156, v124
	s_waitcnt lgkmcnt(1)
	v_mul_f32_e32 v126, v125, v126
	s_waitcnt lgkmcnt(0)
	v_fma_f32 v127, v125, v127, v124
	v_cndmask_b32_e64 v125, v125, v126, s[56:57]
	v_cndmask_b32_e64 v124, v124, v127, s[56:57]
	ds_bpermute_b32 v214, v157, v125
	ds_bpermute_b32 v213, v157, v124
	ds_bpermute_b32 v125, v159, v125
	ds_bpermute_b32 v124, v159, v124
	s_waitcnt lgkmcnt(1)
	v_cndmask_b32_e64 v224, v125, 1.0, s[58:59]
	s_waitcnt lgkmcnt(0)
	v_cndmask_b32_e64 v215, v124, 0, s[58:59]
	ds_read_b128 v[124:127], v180 offset:8704
	s_waitcnt lgkmcnt(0)
	v_mfma_f32_16x16x32_bf16 v[128:131], v[124:127], v[0:3], v[100:103]
	v_mfma_f32_16x16x32_bf16 v[132:135], v[124:127], v[16:19], v[104:107]
	v_mfma_f32_16x16x32_bf16 v[136:139], v[124:127], v[36:39], v[108:111]
	v_mfma_f32_16x16x32_bf16 v[124:127], v[124:127], v[52:55], v[112:115]
	v_mfma_f32_16x16x32_bf16 v[128:131], v[160:163], v[4:7], v[128:131]
	v_mfma_f32_16x16x32_bf16 v[132:135], v[160:163], v[20:23], v[132:135]
	v_mfma_f32_16x16x32_bf16 v[136:139], v[160:163], v[40:43], v[136:139]
	v_mfma_f32_16x16x32_bf16 v[124:127], v[160:163], v[56:59], v[124:127]
	ds_read_b128 v[160:163], v180 offset:8832
	s_waitcnt lgkmcnt(0)
	v_mfma_f32_16x16x32_bf16 v[128:131], v[160:163], v[8:11], v[128:131]
	v_mfma_f32_16x16x32_bf16 v[132:135], v[160:163], v[24:27], v[132:135]
	v_mfma_f32_16x16x32_bf16 v[220:223], v[160:163], v[44:47], v[136:139]
	v_mfma_f32_16x16x32_bf16 v[124:127], v[160:163], v[60:63], v[124:127]
	ds_read_b128 v[160:163], v180 offset:8896
	s_waitcnt lgkmcnt(0)
	v_mfma_f32_16x16x32_bf16 v[128:131], v[160:163], v[12:15], v[128:131]
	s_nop 7
	v_exp_f32_e32 v128, v128
	v_mfma_f32_16x16x32_bf16 v[136:139], v[160:163], v[28:31], v[132:135]
	v_add_f32_e32 v128, 1.0, v128
	v_mfma_f32_16x16x32_bf16 v[132:135], v[160:163], v[48:51], v[220:223]
	v_mfma_f32_16x16x32_bf16 v[124:127], v[160:163], v[64:67], v[124:127]
	s_nop 7
	ds_read_u16 v220, v181 offset:8704
	v_exp_f32_e32 v136, v136
	v_exp_f32_e32 v124, v124
	v_exp_f32_e32 v223, v132
	v_add_f32_e32 v136, 1.0, v136
	v_exp_f32_e32 v239, v129
	v_mul_f32_e32 v221, v128, v136
	v_add_f32_e32 v124, 1.0, v124
	ds_read_b128 v[160:163], v180 offset:13120
	v_add_f32_e32 v223, 1.0, v223
	v_rcp_f32_e32 v221, v221
	v_mul_f32_e32 v237, v223, v124
	v_exp_f32_e32 v240, v137
	v_rcp_f32_e32 v237, v237
	v_mul_f32_e32 v136, v136, v221
	v_mul_f32_e32 v128, v128, v221
	v_add_f32_e32 v239, 1.0, v239
	ds_read_u16 v241, v181 offset:8976
	v_add_f32_e32 v240, 1.0, v240
	v_mul_f32_e32 v136, v185, v136
	v_mul_f32_e32 v124, v124, v237
	v_mul_f32_e32 v221, v239, v240
	v_exp_f32_e32 v136, v136
	v_mul_f32_e32 v124, v186, v124
	v_rcp_f32_e32 v221, v221
	v_exp_f32_e32 v226, v124
	v_fma_f32 v222, -v136, v136, 1.0
	v_mul_f32_e32 v223, v223, v237
	v_mul_f32_e32 v240, v240, v221
	v_sqrt_f32_e32 v222, v222
	v_fma_f32 v238, -v226, v226, 1.0
	v_mul_f32_e32 v240, v185, v240
	s_waitcnt lgkmcnt(2)
; template <int PASS>
; __device__ __forceinline__ void rglru_phase(const Ctx& F, int l, const bf16_t* XRb, bf16_t* GRb, bool latent_only = false) {
;     ...
;             for (int mt = 0; mt < 4; ++mt) {
;                 f32x4 ag[4];
; #pragma unroll
;                 for (int gt = 0; gt < 4; ++gt) { const float nb = (gt & 1) ? nbx[gt >> 1] : nba[gt >> 1]; ag[gt] = (f32x4){nb, nb, nb, nb}; }
; #pragma unroll
;                 for (int ks = 0; ks < 4; ++ks) { const bf16x8 af = *(const LAS bf16x8*)(XT + (mt * 16 + l15) * XT_LD + ks * 32 + 8 * l4);
; #pragma unroll
;                     for (int gt = 0; gt < 4; ++gt) ag[gt] = __builtin_amdgcn_mfma_f32_16x16x32_bf16(af, Bf[gt][ks], ag[gt], 0, 0, 0); }
;                 float ea[2][4], eb[2][4];
; #pragma unroll
;                 for (int r = 0; r < 4; ++r) { const int tok = mt * 16 + 4 * l4 + r;
;                     const float xv = bf2f(XT[tok * XT_LD + cw + l15]);
; #pragma unroll
;                     for (int d = 0; d < 2; ++d) {
;                         const float e1 = 1.0f + __builtin_amdgcn_exp2f(ag[2 * d][r]), e2 = 1.0f + __builtin_amdgcn_exp2f(ag[2 * d + 1][r]);
;                         const float inv = __builtin_amdgcn_rcpf(e1 * e2); const float rgate = e2 * inv, igate = e1 * inv;
;                         const float a = __builtin_amdgcn_exp2f(rgate * cl2[d]);
;                         const float om = fmaf(-a, a, 1.0f);
;                         const float bv = __builtin_amdgcn_sqrtf(om) * (igate * xv);
;                         ea[d][r] = a; eb[d][r] = bv; } }
;     ...
;                         { const float Ap = BPF(lane - 16, A), Bp = BPF(lane - 16, B); if (l4 >= 1) { B = A * Bp + B; A = A * Ap; } }
;                         { const float Ap = BPF(lane - 32, A), Bp = BPF(lane - 32, B); if (l4 >= 2) { B = A * Bp + B; A = A * Ap; } }
;                         const float At = BPF(48 + l15, A), Bt = BPF(48 + l15, B);
;                         float Ae = BPF(lane - 16, A), Be = BPF(lane - 16, B); if (l4 == 0) { Ae = 1.f; Be = 0.f; }
;                         float h = Ae * hF + Be;
; #pragma unroll
;                         for (int r = 0; r < 4; ++r) { h = ea[0][r] * h + eb[0][r]; hfv[mt][r] = h; }
;                         hF = At * hF + Bt;
;                     }
;                     {
;                         float A = ea[1][3], B = eb[1][3];
; #pragma unroll
	v_lshlrev_b32_e32 v220, 16, v220
	v_exp_f32_e32 v125, v125
	v_sqrt_f32_e32 v238, v238
	v_exp_f32_e32 v129, v240
	v_exp_f32_e32 v237, v133
	v_mul_f32_e32 v128, v128, v220
	v_mul_f32_e32 v223, v223, v220
	v_mul_f32_e32 v225, v128, v222
	v_add_f32_e32 v125, 1.0, v125
	v_mul_f32_e32 v227, v223, v238
	v_fma_f32 v222, -v129, v129, 1.0
	v_add_f32_e32 v237, 1.0, v237
	v_sqrt_f32_e32 v222, v222
	v_mul_f32_e32 v220, v237, v125
	v_exp_f32_e32 v223, v138
	v_exp_f32_e32 v240, v130
	s_waitcnt lgkmcnt(0)
	v_lshlrev_b32_e32 v241, 16, v241
	v_mul_f32_e32 v239, v239, v221
	v_rcp_f32_e32 v220, v220
	ds_read_u16 v221, v181 offset:9248
	v_mul_f32_e32 v239, v239, v241
	v_add_f32_e32 v223, 1.0, v223
	v_mul_f32_e32 v228, v239, v222
	v_add_f32_e32 v240, 1.0, v240
	v_mul_f32_e32 v125, v125, v220
	v_mul_f32_e32 v222, v240, v223
	v_mul_f32_e32 v125, v186, v125
	v_mul_f32_e32 v237, v237, v220
	v_rcp_f32_e32 v222, v222
	v_exp_f32_e32 v126, v126
	v_exp_f32_e32 v229, v125
	v_exp_f32_e32 v220, v134
	v_mul_f32_e32 v223, v223, v222
	v_add_f32_e32 v126, 1.0, v126
	v_mul_f32_e32 v241, v237, v241
	v_fma_f32 v238, -v229, v229, 1.0
	v_mul_f32_e32 v223, v185, v223
	v_add_f32_e32 v220, 1.0, v220
	v_sqrt_f32_e32 v238, v238
	v_exp_f32_e32 v128, v223
	v_mul_f32_e32 v237, v220, v126
	v_exp_f32_e32 v127, v127
	v_rcp_f32_e32 v237, v237
	v_mul_f32_e32 v230, v241, v238
	v_fma_f32 v239, -v128, v128, 1.0
	v_exp_f32_e32 v238, v131
	v_sqrt_f32_e32 v239, v239
	v_mul_f32_e32 v126, v126, v237
	v_mul_f32_e32 v220, v220, v237
	v_exp_f32_e32 v223, v139
	s_waitcnt lgkmcnt(0)
	v_lshlrev_b32_e32 v221, 16, v221
	v_mul_f32_e32 v240, v240, v222
	v_exp_f32_e32 v237, v135
	ds_read_u16 v222, v181 offset:9520
	v_mul_f32_e32 v240, v240, v221
	v_add_f32_e32 v238, 1.0, v238
	v_mul_f32_e32 v231, v240, v239
	v_add_f32_e32 v223, 1.0, v223
	v_add_f32_e32 v127, 1.0, v127
	v_mul_f32_e32 v221, v220, v221
	v_mul_f32_e32 v239, v238, v223
	v_add_f32_e32 v237, 1.0, v237
	v_mul_f32_e32 v126, v186, v126
	v_rcp_f32_e32 v239, v239
	v_mul_f32_e32 v220, v237, v127
	v_exp_f32_e32 v232, v126
	v_rcp_f32_e32 v220, v220
	v_mul_f32_e32 v223, v223, v239
	s_waitcnt lgkmcnt(0)
	v_lshlrev_b32_e32 v222, 16, v222
	v_fma_f32 v241, -v232, v232, 1.0
	v_mul_f32_e32 v223, v185, v223
	v_mul_f32_e32 v127, v127, v220
	v_sqrt_f32_e32 v241, v241
	v_exp_f32_e32 v126, v223
	v_mul_f32_e32 v127, v186, v127
	v_mul_f32_e32 v238, v238, v239
	v_exp_f32_e32 v235, v127
	v_mul_f32_e32 v233, v221, v241
	v_fma_f32 v240, -v126, v126, 1.0
	v_mul_f32_e32 v238, v238, v222
	v_sqrt_f32_e32 v240, v240
	v_fma_f32 v241, -v235, v235, 1.0
	v_mul_f32_e32 v237, v237, v220
	v_sqrt_f32_e32 v241, v241
	v_mul_f32_e32 v221, v136, v129
	v_fma_f32 v223, v129, v225, v228
	v_mul_f32_e32 v234, v238, v240
	v_mul_f32_e32 v222, v237, v222
	v_mul_f32_e32 v221, v128, v221
	v_fma_f32 v223, v128, v223, v231
	v_mul_f32_e32 v125, v126, v221
	v_mul_f32_e32 v236, v222, v241
	v_fma_f32 v124, v126, v223, v234
	ds_bpermute_b32 v127, v155, v125
	ds_bpermute_b32 v130, v155, v124
	s_waitcnt lgkmcnt(1)
	v_mul_f32_e32 v127, v125, v127
	s_waitcnt lgkmcnt(0)
	v_fma_f32 v130, v125, v130, v124
	v_cndmask_b32_e64 v125, v125, v127, s[48:49]
	v_cndmask_b32_e64 v124, v124, v130, s[48:49]
	ds_bpermute_b32 v127, v156, v125
	ds_bpermute_b32 v130, v156, v124
	s_waitcnt lgkmcnt(1)
	v_mul_f32_e32 v127, v125, v127
	s_waitcnt lgkmcnt(0)
	v_fma_f32 v130, v125, v130, v124
	v_cndmask_b32_e64 v125, v125, v127, s[50:51]
	v_cndmask_b32_e64 v124, v124, v130, s[50:51]
	ds_bpermute_b32 v127, v158, v125
	ds_bpermute_b32 v241, v158, v124
	ds_bpermute_b32 v125, v155, v125
	ds_bpermute_b32 v124, v155, v124
	s_waitcnt lgkmcnt(2)
	v_fmac_f32_e32 v241, v242, v127
	s_waitcnt lgkmcnt(1)
	v_cndmask_b32_e64 v125, v125, 1.0, s[52:53]
	s_waitcnt lgkmcnt(0)
	v_cndmask_b32_e64 v124, v124, 0, s[52:53]
	v_fmac_f32_e32 v124, v242, v125
	v_fmac_f32_e32 v225, v136, v124
	v_fma_f32 v124, v232, v236, v233
	v_mul_f32_e32 v125, v235, v232
	v_fmac_f32_e32 v228, v129, v225
	v_fma_f32 v124, v229, v124, v230
	v_mul_f32_e32 v125, v229, v125
	v_fmac_f32_e32 v231, v128, v228
	v_fma_f32 v124, v226, v124, v227
	v_mul_f32_e32 v125, v226, v125
	v_fmac_f32_e32 v234, v126, v231
	ds_bpermute_b32 v126, v159, v125
	ds_bpermute_b32 v128, v159, v124
	s_waitcnt lgkmcnt(1)
	v_mul_f32_e32 v126, v125, v126
	s_waitcnt lgkmcnt(0)
	v_fma_f32 v128, v125, v128, v124
	v_cndmask_b32_e64 v125, v125, v126, s[54:55]
	v_cndmask_b32_e64 v124, v124, v128, s[54:55]
	ds_bpermute_b32 v126, v156, v125
	ds_bpermute_b32 v128, v156, v124
	s_waitcnt lgkmcnt(1)
	v_mul_f32_e32 v126, v125, v126
	s_waitcnt lgkmcnt(0)
	v_fma_f32 v128, v125, v128, v124
	v_cndmask_b32_e64 v125, v125, v126, s[56:57]
	v_cndmask_b32_e64 v124, v124, v128, s[56:57]
	ds_bpermute_b32 v238, v157, v125
	ds_bpermute_b32 v237, v157, v124
	ds_bpermute_b32 v125, v159, v125
	ds_bpermute_b32 v124, v159, v124
	s_waitcnt lgkmcnt(1)
	v_cndmask_b32_e64 v240, v125, 1.0, s[58:59]
	s_waitcnt lgkmcnt(0)
	v_cndmask_b32_e64 v239, v124, 0, s[58:59]
	ds_read_b128 v[124:127], v180 offset:13056
	s_waitcnt lgkmcnt(0)
	v_mfma_f32_16x16x32_bf16 v[128:131], v[124:127], v[0:3], v[100:103]
	v_mfma_f32_16x16x32_bf16 v[132:135], v[124:127], v[16:19], v[104:107]
	v_mfma_f32_16x16x32_bf16 v[136:139], v[124:127], v[36:39], v[108:111]
	v_mfma_f32_16x16x32_bf16 v[124:127], v[124:127], v[52:55], v[112:115]
	v_mfma_f32_16x16x32_bf16 v[128:131], v[160:163], v[4:7], v[128:131]
	v_mfma_f32_16x16x32_bf16 v[132:135], v[160:163], v[20:23], v[132:135]
	v_mfma_f32_16x16x32_bf16 v[136:139], v[160:163], v[40:43], v[136:139]
	v_mfma_f32_16x16x32_bf16 v[124:127], v[160:163], v[56:59], v[124:127]
	ds_read_b128 v[160:163], v180 offset:13184
	s_waitcnt lgkmcnt(0)
; template <int PASS>
; __device__ __forceinline__ void rglru_phase(const Ctx& F, int l, const bf16_t* XRb, bf16_t* GRb, bool latent_only = false) {
;     ...
;             for (int mt = 0; mt < 4; ++mt) {
;                 f32x4 ag[4];
; #pragma unroll
;                 for (int gt = 0; gt < 4; ++gt) { const float nb = (gt & 1) ? nbx[gt >> 1] : nba[gt >> 1]; ag[gt] = (f32x4){nb, nb, nb, nb}; }
; #pragma unroll
;                 for (int ks = 0; ks < 4; ++ks) { const bf16x8 af = *(const LAS bf16x8*)(XT + (mt * 16 + l15) * XT_LD + ks * 32 + 8 * l4);
; #pragma unroll
;                     for (int gt = 0; gt < 4; ++gt) ag[gt] = __builtin_amdgcn_mfma_f32_16x16x32_bf16(af, Bf[gt][ks], ag[gt], 0, 0, 0); }
;                 float ea[2][4], eb[2][4];
; #pragma unroll
;                 for (int r = 0; r < 4; ++r) { const int tok = mt * 16 + 4 * l4 + r;
;                     const float xv = bf2f(XT[tok * XT_LD + cw + l15]);
; #pragma unroll
;                     for (int d = 0; d < 2; ++d) {
;                         const float e1 = 1.0f + __builtin_amdgcn_exp2f(ag[2 * d][r]), e2 = 1.0f + __builtin_amdgcn_exp2f(ag[2 * d + 1][r]);
;                         const float inv = __builtin_amdgcn_rcpf(e1 * e2); const float rgate = e2 * inv, igate = e1 * inv;
;                         const float a = __builtin_amdgcn_exp2f(rgate * cl2[d]);
;                         const float om = fmaf(-a, a, 1.0f);
;                         const float bv = __builtin_amdgcn_sqrtf(om) * (igate * xv);
;                         ea[d][r] = a; eb[d][r] = bv; } }
;     ...
;                         { const float Ap = BPF(lane - 16, A), Bp = BPF(lane - 16, B); if (l4 >= 1) { B = A * Bp + B; A = A * Ap; } }
;                         { const float Ap = BPF(lane - 32, A), Bp = BPF(lane - 32, B); if (l4 >= 2) { B = A * Bp + B; A = A * Ap; } }
;                         const float At = BPF(48 + l15, A), Bt = BPF(48 + l15, B);
;                         float Ae = BPF(lane - 16, A), Be = BPF(lane - 16, B); if (l4 == 0) { Ae = 1.f; Be = 0.f; }
;                         float h = Ae * hF + Be;
; #pragma unroll
;                         for (int r = 0; r < 4; ++r) { h = ea[0][r] * h + eb[0][r]; hfv[mt][r] = h; }
;                         hF = At * hF + Bt;
;                     }
;                     {
;                         float A = ea[1][3], B = eb[1][3];
; #pragma unroll
	v_mfma_f32_16x16x32_bf16 v[128:131], v[160:163], v[8:11], v[128:131]
	v_mfma_f32_16x16x32_bf16 v[132:135], v[160:163], v[24:27], v[132:135]
	v_mfma_f32_16x16x32_bf16 v[220:223], v[160:163], v[44:47], v[136:139]
	v_mfma_f32_16x16x32_bf16 v[124:127], v[160:163], v[60:63], v[124:127]
	ds_read_b128 v[160:163], v180 offset:13248
	s_waitcnt lgkmcnt(0)
	v_mfma_f32_16x16x32_bf16 v[136:139], v[160:163], v[12:15], v[128:131]
	s_nop 7
	v_exp_f32_e32 v136, v136
	v_mfma_f32_16x16x32_bf16 v[132:135], v[160:163], v[28:31], v[132:135]
	v_exp_f32_e32 v137, v137
	v_exp_f32_e32 v138, v138
	v_add_f32_e32 v136, 1.0, v136
	v_mfma_f32_16x16x32_bf16 v[128:131], v[160:163], v[48:51], v[220:223]
	v_add_f32_e32 v137, 1.0, v137
	s_nop 2
	v_exp_f32_e32 v132, v132
	v_exp_f32_e32 v133, v133
	v_mfma_f32_16x16x32_bf16 v[124:127], v[160:163], v[64:67], v[124:127]
	ds_read_u16 v160, v181 offset:13056
	v_add_f32_e32 v132, 1.0, v132
	v_mul_f32_e32 v161, v136, v132
	v_rcp_f32_e32 v161, v161
	v_exp_f32_e32 v128, v128
	s_nop 2
	v_exp_f32_e32 v124, v124
	s_waitcnt lgkmcnt(0)
	v_lshlrev_b32_e32 v160, 16, v160
	v_mul_f32_e32 v132, v132, v161
	v_mul_f32_e32 v132, v185, v132
	v_mul_f32_e32 v161, v136, v161
	v_exp_f32_e32 v136, v132
	v_mul_f32_e32 v161, v161, v160
	v_add_f32_e32 v128, 1.0, v128
	v_add_f32_e32 v124, 1.0, v124
	v_fma_f32 v132, -v136, v136, 1.0
	v_sqrt_f32_e32 v132, v132
	v_add_f32_e32 v133, 1.0, v133
	v_exp_f32_e32 v129, v129
	v_exp_f32_e32 v125, v125
	v_mul_f32_e32 v132, v161, v132
	v_mul_f32_e32 v161, v128, v124
	v_rcp_f32_e32 v161, v161
	v_add_f32_e32 v129, 1.0, v129
	v_add_f32_e32 v125, 1.0, v125
	v_exp_f32_e32 v134, v134
	v_mul_f32_e32 v124, v124, v161
	v_mul_f32_e32 v124, v186, v124
	v_exp_f32_e32 v124, v124
	v_mul_f32_e32 v128, v128, v161
	v_mul_f32_e32 v128, v128, v160
	ds_read_u16 v160, v181 offset:13328
	v_fma_f32 v161, -v124, v124, 1.0
	v_sqrt_f32_e32 v161, v161
	v_add_f32_e32 v138, 1.0, v138
	v_add_f32_e32 v134, 1.0, v134
	s_waitcnt lgkmcnt(0)
	v_lshlrev_b32_e32 v160, 16, v160
	v_mul_f32_e32 v128, v128, v161
	v_mul_f32_e32 v161, v137, v133
	v_rcp_f32_e32 v161, v161
	v_exp_f32_e32 v130, v130
	v_exp_f32_e32 v126, v126
	v_exp_f32_e32 v139, v139
	v_mul_f32_e32 v133, v133, v161
	v_mul_f32_e32 v133, v185, v133
	v_mul_f32_e32 v161, v137, v161
	v_exp_f32_e32 v137, v133
	v_mul_f32_e32 v161, v161, v160
	v_add_f32_e32 v130, 1.0, v130
	v_add_f32_e32 v126, 1.0, v126
	v_fma_f32 v133, -v137, v137, 1.0
	v_sqrt_f32_e32 v133, v133
	v_exp_f32_e32 v135, v135
	v_add_f32_e32 v139, 1.0, v139
	v_exp_f32_e32 v131, v131
	v_mul_f32_e32 v133, v161, v133
	v_mul_f32_e32 v161, v129, v125
	v_rcp_f32_e32 v161, v161
	v_add_f32_e32 v135, 1.0, v135
	v_exp_f32_e32 v127, v127
	v_add_f32_e32 v131, 1.0, v131
	v_mul_f32_e32 v125, v125, v161
	v_mul_f32_e32 v125, v186, v125
	v_exp_f32_e32 v125, v125
	v_mul_f32_e32 v129, v129, v161
	v_mul_f32_e32 v129, v129, v160
	ds_read_u16 v160, v181 offset:13600
	v_fma_f32 v161, -v125, v125, 1.0
	v_sqrt_f32_e32 v161, v161
	v_add_f32_e32 v127, 1.0, v127
	s_waitcnt lgkmcnt(0)
	v_lshlrev_b32_e32 v160, 16, v160
	v_mul_f32_e32 v129, v129, v161
	v_mul_f32_e32 v161, v138, v134
	v_rcp_f32_e32 v161, v161
	s_nop 0
	v_mul_f32_e32 v134, v134, v161
	v_mul_f32_e32 v134, v185, v134
	v_mul_f32_e32 v161, v138, v161
	v_exp_f32_e32 v138, v134
	v_mul_f32_e32 v161, v161, v160
	v_fma_f32 v134, -v138, v138, 1.0
	v_sqrt_f32_e32 v134, v134
	s_nop 0
	v_mul_f32_e32 v134, v161, v134
	v_mul_f32_e32 v161, v130, v126
	v_rcp_f32_e32 v161, v161
	s_nop 0
	v_mul_f32_e32 v130, v130, v161
	v_mul_f32_e32 v130, v130, v160
	ds_read_u16 v160, v181 offset:13872
	v_mul_f32_e32 v126, v126, v161
	v_mul_f32_e32 v126, v186, v126
	v_exp_f32_e32 v126, v126
	s_waitcnt lgkmcnt(0)
	s_waitcnt lgkmcnt(0)
	v_lshlrev_b32_e32 v242, 16, v160
	v_mul_f32_e32 v160, v139, v135
	v_rcp_f32_e32 v160, v160
	v_fma_f32 v161, -v126, v126, 1.0
	v_sqrt_f32_e32 v161, v161
	v_mul_f32_e32 v135, v135, v160
	v_mul_f32_e32 v135, v185, v135
	v_exp_f32_e32 v135, v135
	v_mul_f32_e32 v139, v139, v160
	v_mul_f32_e32 v139, v139, v242
	v_mul_f32_e32 v130, v130, v161
	v_fma_f32 v160, -v135, v135, 1.0
	v_sqrt_f32_e32 v160, v160
	v_mul_f32_e32 v161, v136, v137
	v_mul_f32_e32 v161, v138, v161
	v_mul_f32_e32 v161, v135, v161
	v_mul_f32_e32 v139, v139, v160
	v_mul_f32_e32 v160, v131, v127
	v_rcp_f32_e32 v160, v160
	ds_bpermute_b32 v162, v155, v161
	v_mul_f32_e32 v127, v127, v160
	v_mul_f32_e32 v127, v186, v127
	v_exp_f32_e32 v127, v127
	v_mul_f32_e32 v131, v131, v160
	v_mul_f32_e32 v131, v131, v242
	s_waitcnt lgkmcnt(0)
	v_mul_f32_e32 v162, v161, v162
	v_fma_f32 v160, -v127, v127, 1.0
	v_sqrt_f32_e32 v160, v160
	s_nop 0
	v_mul_f32_e32 v131, v131, v160
	v_fma_f32 v160, v137, v132, v133
	v_fma_f32 v160, v138, v160, v134
	v_fma_f32 v160, v135, v160, v139
	ds_bpermute_b32 v163, v155, v160
	s_waitcnt lgkmcnt(0)
	v_fma_f32 v163, v161, v163, v160
	v_cndmask_b32_e64 v161, v161, v162, s[48:49]
	v_cndmask_b32_e64 v160, v160, v163, s[48:49]
	ds_bpermute_b32 v162, v156, v161
	ds_bpermute_b32 v163, v156, v160
	s_waitcnt lgkmcnt(1)
	v_mul_f32_e32 v162, v161, v162
	s_waitcnt lgkmcnt(0)
	v_fma_f32 v163, v161, v163, v160
	v_cndmask_b32_e64 v161, v161, v162, s[50:51]
	v_cndmask_b32_e64 v160, v160, v163, s[50:51]
	ds_bpermute_b32 v161, v155, v161
	ds_bpermute_b32 v160, v155, v160
	s_waitcnt lgkmcnt(1)
	v_cndmask_b32_e64 v161, v161, 1.0, s[52:53]
	s_waitcnt lgkmcnt(0)
	v_cndmask_b32_e64 v160, v160, 0, s[52:53]
	v_fmac_f32_e32 v160, v241, v161
	v_fmac_f32_e32 v132, v136, v160
	v_fmac_f32_e32 v133, v137, v132
	v_fmac_f32_e32 v134, v138, v133
	v_fmac_f32_e32 v139, v135, v134
	v_fma_f32 v135, v126, v131, v130
	v_mul_f32_e32 v136, v127, v126
	v_fma_f32 v135, v125, v135, v129
	v_mul_f32_e32 v136, v125, v136
	v_fma_f32 v135, v124, v135, v128
	v_mul_f32_e32 v136, v124, v136
	ds_bpermute_b32 v137, v159, v136
	ds_bpermute_b32 v138, v159, v135
	ds_read_b32 v160, v187 offset:576
	v_add_u32_e32 v187, 64, v187
	s_waitcnt lgkmcnt(2)
; __device__ __forceinline__ float bflo(unsigned w) { return __uint_as_float(w << 16); }
; __device__ __forceinline__ float bfhi(unsigned w) { return __uint_as_float(w & 0xffff0000u); }
; #define BPF(src_, v_) __uint_as_float(__builtin_amdgcn_ds_bpermute(((src_) & 63) << 2, __float_as_uint(v_)))
; template <int PASS>
; __device__ __forceinline__ void rglru_phase(const Ctx& F, int l, const bf16_t* XRb, bf16_t* GRb, bool latent_only = false) {
;     ...
;                         { const float Ap = BPF(lane + 16, A), Bp = BPF(lane + 16, B); if (l4 <= 2) { B = A * Bp + B; A = A * Ap; } }
;                         { const float Ap = BPF(lane + 32, A), Bp = BPF(lane + 32, B); if (l4 <= 1) { B = A * Bp + B; A = A * Ap; } }
;                         bAt[mt] = BPF(l15, A); bBt[mt] = BPF(l15, B);
;                         float Ae = BPF(lane + 16, A), Be = BPF(lane + 16, B); if (l4 == 3) { Ae = 1.f; Be = 0.f; }
;                         bAe[mt] = Ae; bBe[mt] = Be;
; #pragma unroll
;                         for (int r = 0; r < 4; ++r) { ba_[mt][r] = ea[1][r]; bb_[mt][r] = eb[1][r]; }
;                     }
;                 }
;             }
;             if (PASS == 1) { if (lane < 16) { AGG[((size_t)(b * 2 + 0) * NCH + c) * 1024 + ch] = (f32x2){aggA[0], aggB[0]}; AGG[((size_t)(b * 2 + 1) * NCH + c) * 1024 + ch] = (f32x2){aggA[1], aggB[1]}; } }
;             asm volatile("s_waitcnt lgkmcnt(0)" ::: "memory"); __builtin_amdgcn_wave_barrier();
;             if (PASS == 2) {
;                 float hB = CAR[(1 * 9 + (c - c0)) * 16 + l15];
; #pragma unroll
;     ...
; #pragma unroll
;                     for (int r = 3; r >= 0; --r) { h = ba_[mt][r] * h + bb_[mt][r]; SCF[(r + 4 * mt + 16 * l4) * 17 + l15] = hfv[mt][r] + h; }
;                     hB = bAt[mt] * hB + bBt[mt]; }
;                 asm volatile("s_waitcnt lgkmcnt(0)" ::: "memory"); __builtin_amdgcn_wave_barrier();
;                 const size_t go = (size_t)(seg_row0 + tl0 + lane) * 1024 + blk * 128 + cw;
;                 float u[16];
;                 const int pl = (lane & 3) + 4 * (lane >> 4) + 16 * ((lane >> 2) & 3);
; #pragma unroll
;                 for (int e = 0; e < 16; ++e) { const float hs = SCF[pl * 17 + e]; const unsigned gw = e < 8 ? g0[e >> 1] : g1[(e - 8) >> 1];
;                     u[e] = hs * gelu_tanh((e & 1) ? bfhi(gw) : bflo(gw)); }
	v_mul_f32_e32 v137, v136, v137
	s_waitcnt lgkmcnt(1)
	v_fma_f32 v138, v136, v138, v135
	v_cndmask_b32_e64 v136, v136, v137, s[54:55]
	v_cndmask_b32_e64 v135, v135, v138, s[54:55]
	ds_bpermute_b32 v137, v156, v136
	ds_bpermute_b32 v138, v156, v135
	s_waitcnt lgkmcnt(1)
	v_mul_f32_e32 v137, v136, v137
	s_waitcnt lgkmcnt(0)
	v_fma_f32 v138, v136, v138, v135
	v_cndmask_b32_e64 v136, v136, v137, s[56:57]
	v_cndmask_b32_e64 v135, v135, v138, s[56:57]
	ds_bpermute_b32 v137, v157, v136
	ds_bpermute_b32 v138, v157, v135
	ds_bpermute_b32 v136, v159, v136
	ds_bpermute_b32 v135, v159, v135
	s_waitcnt lgkmcnt(2)
	v_fmac_f32_e32 v138, v160, v137
	s_waitcnt lgkmcnt(1)
	v_cndmask_b32_e64 v136, v136, 1.0, s[58:59]
	s_waitcnt lgkmcnt(0)
	v_cndmask_b32_e64 v135, v135, 0, s[58:59]
	v_fmac_f32_e32 v135, v136, v160
	v_fmac_f32_e32 v131, v127, v135
	v_fmac_f32_e32 v130, v126, v131
	v_fmac_f32_e32 v239, v240, v138
	v_fmac_f32_e32 v129, v125, v130
	v_fmac_f32_e32 v236, v235, v239
	v_fmac_f32_e32 v237, v138, v238
	v_add_f32_e32 v127, v139, v131
	v_add_f32_e32 v126, v134, v130
	v_fmac_f32_e32 v128, v124, v129
	v_fmac_f32_e32 v233, v232, v236
	v_fmac_f32_e32 v215, v224, v237
	ds_write_b32 v182, v127 offset:20480
	ds_write_b32 v183, v126 offset:21432
	v_add_f32_e32 v125, v133, v129
	v_add_f32_e32 v124, v132, v128
	v_add_u32_e32 v126, 0x5000, v183
	v_fmac_f32_e32 v230, v229, v233
	v_fmac_f32_e32 v212, v211, v215
	v_fmac_f32_e32 v213, v237, v214
	ds_write2_b32 v126, v124, v125 offset0:204 offset1:221
	v_add_f32_e32 v124, v234, v236
	v_add_f32_e32 v125, v231, v233
	v_fmac_f32_e32 v227, v226, v230
	v_fmac_f32_e32 v209, v208, v212
	v_fmac_f32_e32 v199, v200, v213
	ds_write2_b32 v126, v125, v124 offset0:170 offset1:187
	v_add_f32_e32 v124, v228, v230
	v_add_f32_e32 v125, v225, v227
	v_fmac_f32_e32 v206, v205, v209
	v_fmac_f32_e32 v198, v197, v199
	ds_write2_b32 v126, v125, v124 offset0:136 offset1:153
	v_add_f32_e32 v124, v210, v212
	v_add_f32_e32 v125, v207, v209
	v_fmac_f32_e32 v203, v202, v206
	v_fmac_f32_e32 v195, v194, v198
	ds_write2_b32 v126, v125, v124 offset0:102 offset1:119
	v_add_f32_e32 v124, v204, v206
	v_add_f32_e32 v125, v201, v203
	v_fmac_f32_e32 v192, v191, v195
	ds_write2_b32 v126, v125, v124 offset0:68 offset1:85
	v_add_f32_e32 v124, v196, v198
	v_add_f32_e32 v125, v193, v195
	v_fmac_f32_e32 v189, v188, v192
	ds_write2_b32 v126, v125, v124 offset0:34 offset1:51
	v_add_f32_e32 v124, v190, v192
	v_add_f32_e32 v32, v32, v189
	ds_write2_b32 v126, v32, v124 offset1:17
	v_add_u32_e32 v32, 0x5000, v184
	s_waitcnt lgkmcnt(0)
	ds_read2_b32 v[124:125], v32 offset1:1
	s_waitcnt vmcnt(0)
	v_lshlrev_b32_e32 v32, 16, v120
	v_mul_f32_e32 v126, 0x3d372713, v32
	v_mul_f32_e32 v126, v126, v32
	v_fma_f32 v126, v126, v32, v32
	v_mul_f32_e32 v126, 0x3f4c422a, v126
	v_add_f32_e32 v126, v126, v126
	v_mul_f32_e32 v126, 0x3fb8aa3b, v126
	v_exp_f32_e32 v126, v126
	v_mul_f32_e32 v32, 0.5, v32
	v_and_b32_e32 v120, 0xffff0000, v120
	v_add_f32_e32 v126, 1.0, v126
	v_rcp_f32_e32 v126, v126
	s_nop 0
	v_fma_f32 v126, v126, -2.0, 1.0
	v_add_f32_e32 v126, 1.0, v126
	v_mul_f32_e32 v32, v32, v126
	s_waitcnt lgkmcnt(0)
	v_mul_f32_e32 v32, v32, v124
	v_mul_f32_e32 v124, 0x3d372713, v120
	v_mul_f32_e32 v124, v124, v120
	v_fma_f32 v124, v124, v120, v120
	v_mul_f32_e32 v124, 0x3f4c422a, v124
	v_add_f32_e32 v124, v124, v124
	v_mul_f32_e32 v124, 0x3fb8aa3b, v124
	v_exp_f32_e32 v124, v124
	v_mul_f32_e32 v120, 0.5, v120
	v_add_f32_e32 v124, 1.0, v124
	v_rcp_f32_e32 v124, v124
	s_nop 0
	v_fma_f32 v124, v124, -2.0, 1.0
	v_add_f32_e32 v124, 1.0, v124
	v_mul_f32_e32 v120, v120, v124
	v_mul_f32_e32 v124, v120, v125
	v_add_u32_e32 v120, 0x5008, v184
	ds_read2_b32 v[126:127], v120 offset1:1
	v_lshlrev_b32_e32 v120, 16, v121
	v_mul_f32_e32 v125, 0x3d372713, v120
	v_mul_f32_e32 v125, v125, v120
	v_fma_f32 v125, v125, v120, v120
	v_mul_f32_e32 v125, 0x3f4c422a, v125
	v_add_f32_e32 v125, v125, v125
	v_mul_f32_e32 v125, 0x3fb8aa3b, v125
	v_exp_f32_e32 v125, v125
	v_mul_f32_e32 v120, 0.5, v120
	v_add_f32_e32 v125, 1.0, v125
	v_rcp_f32_e32 v125, v125
	s_nop 0
	v_fma_f32 v125, v125, -2.0, 1.0
	v_add_f32_e32 v125, 1.0, v125
	v_mul_f32_e32 v120, v120, v125
	s_waitcnt lgkmcnt(0)
	v_mul_f32_e32 v125, v120, v126
	v_and_b32_e32 v120, 0xffff0000, v121
	v_mul_f32_e32 v121, 0x3d372713, v120
	v_mul_f32_e32 v121, v121, v120
	v_fma_f32 v121, v121, v120, v120
	v_mul_f32_e32 v121, 0x3f4c422a, v121
	v_add_f32_e32 v121, v121, v121
	v_mul_f32_e32 v121, 0x3fb8aa3b, v121
	v_exp_f32_e32 v121, v121
	v_mul_f32_e32 v120, 0.5, v120
	v_add_f32_e32 v121, 1.0, v121
	v_rcp_f32_e32 v121, v121
	s_nop 0
	v_fma_f32 v121, v121, -2.0, 1.0
	v_add_f32_e32 v121, 1.0, v121
	v_mul_f32_e32 v120, v120, v121
	v_mul_f32_e32 v126, v120, v127
	v_lshlrev_b32_e32 v127, 16, v122
	v_mul_f32_e32 v128, 0x3d372713, v127
	v_mul_f32_e32 v128, v128, v127
	v_fma_f32 v128, v128, v127, v127
	v_mul_f32_e32 v128, 0x3f4c422a, v128
	v_add_f32_e32 v128, v128, v128
	v_mul_f32_e32 v128, 0x3fb8aa3b, v128
	v_exp_f32_e32 v128, v128
	v_add_u32_e32 v120, 0x5010, v184
	ds_read2_b32 v[120:121], v120 offset1:1
	v_mul_f32_e32 v127, 0.5, v127
	v_add_f32_e32 v128, 1.0, v128
	v_rcp_f32_e32 v128, v128
	s_nop 0
	v_fma_f32 v128, v128, -2.0, 1.0
	v_add_f32_e32 v128, 1.0, v128
	v_mul_f32_e32 v127, v127, v128
	s_waitcnt lgkmcnt(0)
; __device__ __forceinline__ unsigned cvt_pk_bf16(float lo, float hi) { unsigned r; asm volatile("v_cvt_pk_bf16_f32 %0, %1, %2" : "=v"(r) : "v"(lo), "v"(hi)); return r; }
; __device__ __forceinline__ float bflo(unsigned w) { return __uint_as_float(w << 16); }
; __device__ __forceinline__ float bfhi(unsigned w) { return __uint_as_float(w & 0xffff0000u); }
; __device__ __forceinline__ float gelu_tanh(float x) { const float u = 0.7978845608028654f * (x + 0.044715f * x * x * x); const float t = 1.0f - 2.0f * __builtin_amdgcn_rcpf(1.0f + __expf(2.0f * u)); return 0.5f * x * (1.0f + t); }
; template <int PASS>
; __device__ __forceinline__ void rglru_phase(const Ctx& F, int l, const bf16_t* XRb, bf16_t* GRb, bool latent_only = false) {
;     ...
;                 for (int e = 0; e < 16; ++e) { const float hs = SCF[pl * 17 + e]; const unsigned gw = e < 8 ? g0[e >> 1] : g1[(e - 8) >> 1];
;                     u[e] = hs * gelu_tanh((e & 1) ? bfhi(gw) : bflo(gw)); }
;                 u32x4 o0, o1; o0.x = cvt_pk_bf16(u[0], u[1]); o0.y = cvt_pk_bf16(u[2], u[3]); o0.z = cvt_pk_bf16(u[4], u[5]); o0.w = cvt_pk_bf16(u[6], u[7]);
;                 o1.x = cvt_pk_bf16(u[8], u[9]); o1.y = cvt_pk_bf16(u[10], u[11]); o1.z = cvt_pk_bf16(u[12], u[13]); o1.w = cvt_pk_bf16(u[14], u[15]);
;                 *(u32x4*)(GRb + go) = o0; *(u32x4*)(GRb + go + 8) = o1;
	v_mul_f32_e32 v127, v127, v120
	v_and_b32_e32 v120, 0xffff0000, v122
	v_mul_f32_e32 v122, 0x3d372713, v120
	v_mul_f32_e32 v122, v122, v120
	v_fma_f32 v122, v122, v120, v120
	v_mul_f32_e32 v122, 0x3f4c422a, v122
	v_add_f32_e32 v122, v122, v122
	v_mul_f32_e32 v122, 0x3fb8aa3b, v122
	v_lshlrev_b32_e32 v128, 16, v123
	v_exp_f32_e32 v122, v122
	v_mul_f32_e32 v129, 0x3d372713, v128
	v_mul_f32_e32 v129, v129, v128
	v_fma_f32 v129, v129, v128, v128
	v_mul_f32_e32 v129, 0x3f4c422a, v129
	v_add_f32_e32 v122, 1.0, v122
	v_add_f32_e32 v129, v129, v129
	v_rcp_f32_e32 v122, v122
	v_mul_f32_e32 v129, 0x3fb8aa3b, v129
	v_exp_f32_e32 v129, v129
	v_mul_f32_e32 v120, 0.5, v120
	v_fma_f32 v122, v122, -2.0, 1.0
	v_add_f32_e32 v122, 1.0, v122
	v_add_f32_e32 v129, 1.0, v129
	v_mul_f32_e32 v120, v120, v122
	v_rcp_f32_e32 v129, v129
	v_mul_f32_e32 v122, v120, v121
	v_add_u32_e32 v120, 0x5018, v184
	ds_read2_b32 v[120:121], v120 offset1:1
	v_fma_f32 v129, v129, -2.0, 1.0
	v_mul_f32_e32 v128, 0.5, v128
	v_add_f32_e32 v129, 1.0, v129
	v_mul_f32_e32 v128, v128, v129
	v_and_b32_e32 v123, 0xffff0000, v123
	s_waitcnt lgkmcnt(0)
	v_mul_f32_e32 v120, v128, v120
	v_mul_f32_e32 v128, 0x3d372713, v123
	v_mul_f32_e32 v128, v128, v123
	v_fma_f32 v128, v128, v123, v123
	v_mul_f32_e32 v128, 0x3f4c422a, v128
	v_add_f32_e32 v128, v128, v128
	v_mul_f32_e32 v128, 0x3fb8aa3b, v128
	v_exp_f32_e32 v128, v128
	v_mul_f32_e32 v123, 0.5, v123
	v_add_f32_e32 v128, 1.0, v128
	v_rcp_f32_e32 v128, v128
	s_nop 0
	v_fma_f32 v128, v128, -2.0, 1.0
	v_add_f32_e32 v128, 1.0, v128
	v_mul_f32_e32 v123, v123, v128
	v_mul_f32_e32 v121, v123, v121
	v_add_u32_e32 v123, 0x5020, v184
	ds_read2_b32 v[128:129], v123 offset1:1
	v_lshlrev_b32_e32 v123, 16, v116
	v_mul_f32_e32 v130, 0x3d372713, v123
	v_mul_f32_e32 v130, v130, v123
	v_fma_f32 v130, v130, v123, v123
	v_mul_f32_e32 v130, 0x3f4c422a, v130
	v_add_f32_e32 v130, v130, v130
	v_mul_f32_e32 v130, 0x3fb8aa3b, v130
	v_exp_f32_e32 v130, v130
	v_mul_f32_e32 v123, 0.5, v123
	v_and_b32_e32 v116, 0xffff0000, v116
	v_add_f32_e32 v130, 1.0, v130
	v_rcp_f32_e32 v130, v130
	s_nop 0
	v_fma_f32 v130, v130, -2.0, 1.0
	v_add_f32_e32 v130, 1.0, v130
	v_mul_f32_e32 v123, v123, v130
	s_waitcnt lgkmcnt(0)
	v_mul_f32_e32 v123, v123, v128
	v_mul_f32_e32 v128, 0x3d372713, v116
	v_mul_f32_e32 v128, v128, v116
	v_fma_f32 v128, v128, v116, v116
	v_mul_f32_e32 v128, 0x3f4c422a, v128
	v_add_f32_e32 v128, v128, v128
	v_mul_f32_e32 v128, 0x3fb8aa3b, v128
	v_exp_f32_e32 v128, v128
	v_mul_f32_e32 v116, 0.5, v116
	v_add_f32_e32 v128, 1.0, v128
	v_rcp_f32_e32 v128, v128
	s_nop 0
	v_fma_f32 v128, v128, -2.0, 1.0
	v_add_f32_e32 v128, 1.0, v128
	v_mul_f32_e32 v116, v116, v128
	v_mul_f32_e32 v128, v116, v129
	v_add_u32_e32 v116, 0x5028, v184
	ds_read2_b32 v[130:131], v116 offset1:1
	v_lshlrev_b32_e32 v116, 16, v117
	v_mul_f32_e32 v129, 0x3d372713, v116
	v_mul_f32_e32 v129, v129, v116
	v_fma_f32 v129, v129, v116, v116
	v_mul_f32_e32 v129, 0x3f4c422a, v129
	v_add_f32_e32 v129, v129, v129
	v_mul_f32_e32 v129, 0x3fb8aa3b, v129
	v_exp_f32_e32 v129, v129
	v_mul_f32_e32 v116, 0.5, v116
	v_add_f32_e32 v129, 1.0, v129
	v_rcp_f32_e32 v129, v129
	s_nop 0
	v_fma_f32 v129, v129, -2.0, 1.0
	v_add_f32_e32 v129, 1.0, v129
	v_mul_f32_e32 v116, v116, v129
	s_waitcnt lgkmcnt(0)
	v_mul_f32_e32 v129, v116, v130
	v_and_b32_e32 v116, 0xffff0000, v117
	v_mul_f32_e32 v117, 0x3d372713, v116
	v_mul_f32_e32 v117, v117, v116
	v_fma_f32 v117, v117, v116, v116
	v_mul_f32_e32 v117, 0x3f4c422a, v117
	v_add_f32_e32 v117, v117, v117
	v_mul_f32_e32 v117, 0x3fb8aa3b, v117
	v_exp_f32_e32 v117, v117
	v_mul_f32_e32 v116, 0.5, v116
	v_add_f32_e32 v117, 1.0, v117
	v_rcp_f32_e32 v117, v117
	s_nop 0
	v_fma_f32 v117, v117, -2.0, 1.0
	v_add_f32_e32 v117, 1.0, v117
	v_mul_f32_e32 v116, v116, v117
	v_mul_f32_e32 v130, v116, v131
	v_lshlrev_b32_e32 v131, 16, v118
	v_mul_f32_e32 v132, 0x3d372713, v131
	v_mul_f32_e32 v132, v132, v131
	v_fma_f32 v132, v132, v131, v131
	v_mul_f32_e32 v132, 0x3f4c422a, v132
	v_add_f32_e32 v132, v132, v132
	v_mul_f32_e32 v132, 0x3fb8aa3b, v132
	v_exp_f32_e32 v132, v132
	v_add_u32_e32 v116, 0x5030, v184
	ds_read2_b32 v[116:117], v116 offset1:1
	v_mul_f32_e32 v131, 0.5, v131
	v_add_f32_e32 v132, 1.0, v132
	v_rcp_f32_e32 v132, v132
	s_nop 0
	v_fma_f32 v132, v132, -2.0, 1.0
	v_add_f32_e32 v132, 1.0, v132
	v_mul_f32_e32 v131, v131, v132
	s_waitcnt lgkmcnt(0)
	v_mul_f32_e32 v131, v131, v116
	v_and_b32_e32 v116, 0xffff0000, v118
	v_mul_f32_e32 v118, 0x3d372713, v116
	v_mul_f32_e32 v118, v118, v116
	v_fma_f32 v118, v118, v116, v116
	v_mul_f32_e32 v118, 0x3f4c422a, v118
	v_add_f32_e32 v118, v118, v118
	v_mul_f32_e32 v118, 0x3fb8aa3b, v118
	v_exp_f32_e32 v118, v118
	v_mul_f32_e32 v116, 0.5, v116
	v_add_f32_e32 v118, 1.0, v118
	v_rcp_f32_e32 v118, v118
	s_nop 0
	v_fma_f32 v118, v118, -2.0, 1.0
	v_add_f32_e32 v118, 1.0, v118
	v_mul_f32_e32 v116, v116, v118
	v_lshlrev_b32_e32 v118, 16, v119
	v_mul_f32_e32 v133, 0x3d372713, v118
	v_mul_f32_e32 v133, v133, v118
	v_fma_f32 v133, v133, v118, v118
	v_mul_f32_e32 v133, 0x3f4c422a, v133
	v_add_f32_e32 v133, v133, v133
	v_mul_f32_e32 v133, 0x3fb8aa3b, v133
	v_exp_f32_e32 v133, v133
	v_mul_f32_e32 v132, v116, v117
	v_add_u32_e32 v116, 0x5038, v184
	ds_read2_b32 v[116:117], v116 offset1:1
	v_add_f32_e32 v133, 1.0, v133
	v_rcp_f32_e32 v133, v133
	v_mul_f32_e32 v118, 0.5, v118
	v_fma_f32 v133, v133, -2.0, 1.0
	v_add_f32_e32 v133, 1.0, v133
	v_mul_f32_e32 v118, v118, v133
	s_waitcnt lgkmcnt(0)
	v_mul_f32_e32 v133, v118, v116
	v_and_b32_e32 v116, 0xffff0000, v119
	v_mul_f32_e32 v118, 0x3d372713, v116
	v_mul_f32_e32 v118, v118, v116
	v_fma_f32 v118, v118, v116, v116
	v_mul_f32_e32 v118, 0x3f4c422a, v118
	v_add_f32_e32 v118, v118, v118
	v_mul_f32_e32 v118, 0x3fb8aa3b, v118
	v_exp_f32_e32 v118, v118
	v_mul_f32_e32 v116, 0.5, v116
	v_add_f32_e32 v118, 1.0, v118
	v_rcp_f32_e32 v118, v118
	s_nop 0
	v_fma_f32 v118, v118, -2.0, 1.0
	v_add_f32_e32 v118, 1.0, v118
	v_mul_f32_e32 v116, v116, v118
	v_mul_f32_e32 v134, v116, v117
	v_cvt_pk_bf16_f32 v116, v32, v124
	v_cvt_pk_bf16_f32 v117, v125, v126
	v_cvt_pk_bf16_f32 v118, v127, v122
	v_cvt_pk_bf16_f32 v119, v120, v121
	v_cvt_pk_bf16_f32 v120, v123, v128
	v_cvt_pk_bf16_f32 v121, v129, v130
	v_cvt_pk_bf16_f32 v122, v131, v132
	v_cvt_pk_bf16_f32 v123, v133, v134
	global_store_dwordx4 v[34:35], v[116:119], off
	global_store_dwordx4 v[34:35], v[120:123], off offset:16
	s_cbranch_vccnz .LBB0_453
